# code placement: one 4-byte pad before the hand-written sparse/indexer code so both hot loop heads sit at 0 mod 8 bytes
# baseline (speedup 1.0000x reference)
; #define LAS __attribute__((address_space(3)))
; __device__ __forceinline__ void sparse_unit7(const bf16_t* QKV, const unsigned char* K8, const unsigned char* V8, const int (&selv)[4], bf16_t* OB, LAS unsigned char* wl, int t, int h, int lane) {
;     LAS int* wsel = (LAS int*)wl; LAS unsigned* otw = (LAS unsigned*)(wl + 1024); LAS float* ptw = (LAS float*)(wl + 2048);
;     const int n16 = lane & 15, slab = lane >> 4, half = lane >> 5, l4 = (lane & 31) * 4;
;     const bf16_t* qrow = QKV + (size_t)t * QKVW + COL_BQ + h * 128 + 16 * slab;
;     long qa[4];
; #pragma unroll
;     for (int ks = 0; ks < 4; ++ks) { const u32x4 raw = *(const u32x4*)(qrow + 8 * (ks & 1) + 64 * (ks >> 1)); const unsigned w[4] = {raw.x, raw.y, raw.z, raw.w}; float x[8];
; #pragma unroll
;         for (int i = 0; i < 4; ++i) { x[2 * i] = bf2f(w[i] & 0xffffu); x[2 * i + 1] = __builtin_bit_cast(float, w[i] & 0xffff0000u); }
;         const u32x2 f = to_fp8x8(x); qa[ks] = (long)(((unsigned long long)f.y << 32) | f.x); }
;     const unsigned char* K8h = K8 + h * 128; const unsigned char* V8h = V8 + h * 128;
; __global__ void __launch_bounds__(NTHREADS, 2) mega(Args a) {
;     ...
;                 const int h = blockIdx.x & 7, qg = (blockIdx.x >> 3) * NWAVES + wave, nqg = ((G + 7) >> 3) * NWAVES;
;                 for (int u = gw; u < SEQ * 4; u += NGW) dilated_merge(OG, LSE, OA, u >> 2, u & 3, lane);
;                 for (int rep = 0; rep < REP_SP; ++rep)
;                 if ((G & 7) == 0) { int seln[4];
; #pragma unroll
;                     for (int s = 0; s < 4; ++s) seln[s] = (int)SEL[(size_t)min(qg, SEQ - 1) * 256 + 64 * s + lane];
;                     for (int t = qg; t < SEQ; t += nqg) { int selc[4];
; #pragma unroll
;                         for (int s = 0; s < 4; ++s) selc[s] = seln[s];
;                         const int tn = min(t + nqg, SEQ - 1);
; #pragma unroll
;                         for (int s = 0; s < 4; ++s) seln[s] = (int)SEL[(size_t)tn * 256 + 64 * s + lane];
;                         sparse_unit7(QKV, K8, V8, selc, OB, lds + wave * 4096, t, h, lane); } }
.LBB0_160:
.LBB0_161:
	s_nop 0
	v_readlane_b32 s0, v251, 0
	v_readlane_b32 s1, v250, 18
	s_nop 3
	s_and_b32 s4, s0, 7
	s_and_b32 s5, s0, -8
	s_add_i32 s34, s5, s1
	s_add_i32 s48, s94, 7
	s_and_b32 s48, s48, -8
	s_add_u32 s38, s90, 0x28600000
	s_addc_u32 s39, s91, 0
	s_lshl_b32 s5, s4, 8
	s_add_u32 s5, s5, 0x12302400
	s_add_u32 s40, s90, s5
	s_addc_u32 s41, s91, 0
	s_lshl_b32 s5, s4, 21
	s_add_u32 s0, s5, 0x3cf00000
	s_add_u32 s42, s90, s0
	s_addc_u32 s43, s91, 0
	s_add_u32 s0, s5, 0x3df00000
	s_add_u32 s44, s90, s0
	s_addc_u32 s45, s91, 0
	s_lshl_b32 s5, s4, 8
	s_add_u32 s0, s5, 0x29e00000
	s_add_u32 s46, s90, s0
	s_addc_u32 s47, s91, 0
	s_lshl_b32 s0, s1, 13
	v_and_b32_e32 v218, 15, v182
	v_lshrrev_b32_e32 v219, 4, v182
	v_and_b32_e32 v246, 7, v182
	v_lshrrev_b32_e32 v247, 3, v182
	v_lshlrev_b32_e32 v200, 6, v247
	v_lshlrev_b32_e32 v201, 5, v219
	v_xor_b32_e32 v248, v246, v247
	v_lshlrev_b32_e32 v202, 4, v248
	v_lshlrev_b32_e32 v203, 4, v246
	v_lshl_add_u32 v224, v182, 4, s0
	v_and_b32_e32 v248, 7, v218
	v_lshrrev_b32_e32 v249, 3, v218
	v_lshlrev_b32_e32 v227, 4, v249
	v_lshlrev_b32_e32 v225, 10, v249
	v_lshl_add_u32 v225, v248, 7, v225
	v_add_u32_e32 v225, s0, v225
	v_xor_b32_e32 v217, v219, v248
	v_xor_b32_e32 v226, 4, v217
	v_lshl_add_u32 v226, v226, 4, v225
	v_lshl_add_u32 v225, v217, 4, v225
	v_lshlrev_b32_e32 v217, 5, v248
	v_lshl_add_u32 v217, v219, 3, v217
	v_sub_u32_e32 v216, v217, v161
	v_lshlrev_b32_e32 v216, 1, v216
	v_add_u32_e32 v217, v217, v249
	v_lshlrev_b32_e32 v248, 4, v218
	v_lshl_add_u32 v248, v219, 2, v248
	v_lshrrev_b32_e32 v249, 1, v218
	v_lshl_add_u32 v248, v249, 2, v248
	v_lshlrev_b32_e32 v213, 2, v248
	s_add_i32 s1, s0, 0x1000
	v_add_u32_e32 v213, s1, v213
	v_mul_u32_u24_e32 v214, 0x90, v247
	v_add_u32_e32 v214, s1, v214
	v_lshlrev_b32_e32 v215, 5, v246
	v_lshl_add_u32 v215, v219, 3, v215
	v_cmp_eq_u32_e64 s[8:9], 0, v219
	v_cmp_eq_u32_e64 s[10:11], 1, v219
	v_cmp_eq_u32_e64 s[16:17], 2, v219
	v_cmp_eq_u32_e64 s[22:23], 3, v219
	s_lshl_b32 s0, s34, 9
	s_add_u32 s0, s38, s0
	s_addc_u32 s1, s39, 0
	s_mul_i32 s4, s34, 0x3c00
	s_add_u32 s4, s40, s4
	s_addc_u32 s5, s41, 0
	global_load_dwordx4 v[96:99], v200, s[0:1]
	global_load_dwordx4 v[100:103], v200, s[0:1] offset:16
	global_load_dwordx4 v[104:107], v200, s[0:1] offset:32
	global_load_dwordx4 v[108:111], v200, s[0:1] offset:48
	global_load_dwordx4 v[220:223], v216, s[0:1]
	global_load_dwordx4 v[230:233], v201, s[4:5]
	global_load_dwordx4 v[234:237], v201, s[4:5] offset:16
	global_load_dwordx4 v[238:241], v201, s[4:5] offset:128
	global_load_dwordx4 v[242:245], v201, s[4:5] offset:144
	s_waitcnt vmcnt(0)
	s_nop 0
